# inproj XCD mapping variant with nt stores: 12 N-tiles x a quarter of the M-tiles per XCD (xn row tile fetched into 2 L2s, 3 MB of weights per XCD)
# baseline (speedup 1.0000x reference)
; DI void phase_inproj(const Params& p, int l, char* smem, int tid) {
;     ...
;   for (int it = blockIdx.x; it < 272 * 24; it += gridDim.x) {
;     const int mt = it / 24, nt = it % 24, m0 = mt * 128, n0 = nt * 128;
;     f32x16 acc[2][2]; zero_acc<2>(acc);
;     gemm_main<2>(p.xn + (size_t)m0 * 1024, 1024, Wt + (size_t)n0 * 1024, 1024, 1024, acc, s, tid);
.Lipx_wait:
	s_barrier
	ds_read_b32 v115, v116
	s_waitcnt lgkmcnt(0)
	v_readfirstlane_b32 s12, v115
	v_readfirstlane_b32 s17, v114
	s_lshr_b32 s2, s16, 1
	s_lshl_b32 s2, s2, 10
	s_or_b32 s17, s17, s2
	s_and_b32 s2, s16, 1
	s_mul_i32 s2, s2, 12
	s_lshl_b32 s2, s2, 18
	s_or_b32 s17, s17, s2
	s_bitset1_b32 s17, 31
.Lipx_flat:
	s_movk_i32 s2, 0x1980
	s_bitcmp1_b32 s17, 31
	s_cselect_b32 s2, 0x330, s2
	s_cmp_lt_u32 s12, s2
	s_cbranch_scc0 .Lip_done
	s_mul_hi_u32 s0, s12, 0xaaaaaaab
	s_bitcmp1_b32 s17, 31
	s_cselect_b32 s2, 3, 4
	s_lshr_b32 s0, s0, s2
	s_bitcmp1_b32 s17, 31
	s_cselect_b32 s2, 12, 24
	s_mul_i32 s2, s0, s2
	s_sub_u32 s1, s12, s2
	s_bfe_u32 s2, s17, 0x80012
	s_add_u32 s1, s1, s2
	s_bitcmp1_b32 s17, 31
	s_cselect_b32 s2, 2, 0
	s_lshl_b32 s0, s0, s2
	s_bfe_u32 s2, s17, 0x8000a
	s_add_u32 s0, s0, s2
	s_lshl_b32 s2, s0, 18
	s_add_u32 s4, s96, s2
	s_addc_u32 s5, s97, 0
	s_lshl_b32 s2, s1, 18
	s_add_u32 s8, s14, s2
	s_addc_u32 s9, s15, 0
	s_add_u32 m0, s10, 0x0
	s_nop 0
	global_load_lds_dwordx4 v98, s[4:5]
	s_add_u32 m0, s10, 0x400
	s_nop 0
	global_load_lds_dwordx4 v99, s[4:5]
	s_add_u32 m0, s10, 0x800
	s_nop 0
	global_load_lds_dwordx4 v100, s[4:5]
	s_add_u32 m0, s10, 0xc00
	s_nop 0
	global_load_lds_dwordx4 v101, s[4:5]
	s_add_u32 m0, s10, 0x4000
	s_nop 0
	global_load_lds_dwordx4 v98, s[8:9]
	s_add_u32 m0, s10, 0x4400
	s_nop 0
	global_load_lds_dwordx4 v99, s[8:9]
	s_add_u32 m0, s10, 0x4800
	s_nop 0
	global_load_lds_dwordx4 v100, s[8:9]
	s_add_u32 m0, s10, 0x4c00
	s_nop 0
	global_load_lds_dwordx4 v101, s[8:9]
	s_add_u32 s4, s4, 128
	s_addc_u32 s5, s5, 0
	s_add_u32 s8, s8, 128
	s_addc_u32 s9, s9, 0
.Lip_item:
	s_mul_hi_u32 s0, s12, 0xaaaaaaab
	s_bitcmp1_b32 s17, 31
	s_cselect_b32 s2, 3, 4
	s_lshr_b32 s0, s0, s2
	s_bitcmp1_b32 s17, 31
	s_cselect_b32 s2, 12, 24
	s_mul_i32 s2, s0, s2
	s_sub_u32 s1, s12, s2
	s_bfe_u32 s2, s17, 0x80012
	s_add_u32 s1, s1, s2
	s_bitcmp1_b32 s17, 31
	s_cselect_b32 s2, 2, 0
	s_lshl_b32 s0, s0, s2
	s_bfe_u32 s2, s17, 0x8000a
	s_add_u32 s0, s0, s2
	s_mov_b32 s94, 0

; #define G_STORE(S, bf) { *(uint4*)&s->a[bf][srow][skc] = S##a0; *(uint4*)&s->a[bf][srow + 32][skc] = S##a1; \
;     if (MB == 2) { *(uint4*)&s->a[bf][srow + 64][skc] = S##a2; *(uint4*)&s->a[bf][srow + 96][skc] = S##a3; } \
;     *(uint4*)&s->b[bf][srow][skc] = S##b0; *(uint4*)&s->b[bf][srow + 32][skc] = S##b1; *(uint4*)&s->b[bf][srow + 64][skc] = S##b2; *(uint4*)&s->b[bf][srow + 96][skc] = S##b3; }
; template <int MB, bool PF2 = true>
; DI void gemm_main(const u16* __restrict__ A, int lda, const u16* __restrict__ B, int ldb, int K, f32x16 (&acc)[MB][2], GemmLds* s, int tid) {
;     ...
;   for (int kt = 0; kt < KT; kt += 2) {
;     { const int k2 = min((kt + 2) * 64, klast); G_LOAD(q, k2); }
;     __builtin_amdgcn_sched_barrier(0);
;     G_COMPUTE(0);
;     G_STORE(p, 1);
;     __syncthreads();
;     { const int k3 = min((kt + 3) * 64, klast); G_LOAD(p, k3); }
;     __builtin_amdgcn_sched_barrier(0);
;     G_COMPUTE(1);
;     G_STORE(q, 0);
;     __syncthreads();
; DI void phase_inproj(const Params& p, int l, char* smem, int tid) {
;     ...
;   for (int it = blockIdx.x; it < 272 * 24; it += gridDim.x) {
;     const int mt = it / 24, nt = it % 24, m0 = mt * 128, n0 = nt * 128;
;     f32x16 acc[2][2]; zero_acc<2>(acc);
;     gemm_main<2>(p.xn + (size_t)m0 * 1024, 1024, Wt + (size_t)n0 * 1024, 1024, 1024, acc, s, tid);
.Lip_last:
	s_and_b32 s6, s17, 0x3ff
	s_add_u32 s6, s12, s6
	s_movk_i32 s2, 0x1980
	s_bitcmp1_b32 s17, 31
	s_cselect_b32 s2, 0x330, s2
	s_cmp_lt_u32 s6, s2
	s_cbranch_scc0 .Lip_nopf
	s_mul_hi_u32 s2, s6, 0xaaaaaaab
	s_bitcmp1_b32 s17, 31
	s_cselect_b32 s4, 3, 4
	s_lshr_b32 s2, s2, s4
	s_bitcmp1_b32 s17, 31
	s_cselect_b32 s4, 12, 24
	s_mul_i32 s4, s2, s4
	s_sub_u32 s3, s6, s4
	s_bfe_u32 s4, s17, 0x80012
	s_add_u32 s3, s3, s4
	s_bitcmp1_b32 s17, 31
	s_cselect_b32 s4, 2, 0
	s_lshl_b32 s2, s2, s4
	s_bfe_u32 s4, s17, 0x8000a
	s_add_u32 s2, s2, s4
	s_lshl_b32 s2, s2, 18
	s_add_u32 s4, s96, s2
	s_addc_u32 s5, s97, 0
	s_lshl_b32 s3, s3, 18
	s_add_u32 s8, s14, s3
	s_addc_u32 s9, s15, 0
	ds_read_b128 v[82:85], v103 offset:32768
	ds_read_b128 v[90:93], v107 offset:32768
	ds_read_b128 v[86:89], v103 offset:36864
	ds_read_b128 v[94:97], v107 offset:36864
	s_waitcnt lgkmcnt(4)
	s_add_u32 m0, s10, 0x0
	v_mfma_f32_32x32x16_bf16 v[2:17], v[74:77], v[66:69], v[2:17]
	global_load_lds_dwordx4 v98, s[4:5]
	s_add_u32 m0, s10, 0x400
	v_mfma_f32_32x32x16_bf16 v[18:33], v[78:81], v[66:69], v[18:33]
	global_load_lds_dwordx4 v99, s[4:5]
	s_add_u32 m0, s10, 0x800
	v_mfma_f32_32x32x16_bf16 v[34:49], v[74:77], v[70:73], v[34:49]
	global_load_lds_dwordx4 v100, s[4:5]
	s_add_u32 m0, s10, 0xc00
	v_mfma_f32_32x32x16_bf16 v[50:65], v[78:81], v[70:73], v[50:65]
	global_load_lds_dwordx4 v101, s[4:5]
	s_add_u32 s4, s4, 128
	s_addc_u32 s5, s5, 0
	ds_read_b128 v[66:69], v104 offset:32768
	ds_read_b128 v[74:77], v108 offset:32768
	ds_read_b128 v[70:73], v104 offset:36864
	ds_read_b128 v[78:81], v108 offset:36864
	s_waitcnt lgkmcnt(4)
	s_add_u32 m0, s10, 0x4000
	v_mfma_f32_32x32x16_bf16 v[2:17], v[90:93], v[82:85], v[2:17]
	global_load_lds_dwordx4 v98, s[8:9]
	s_add_u32 m0, s10, 0x4400
	v_mfma_f32_32x32x16_bf16 v[18:33], v[94:97], v[82:85], v[18:33]
	global_load_lds_dwordx4 v99, s[8:9]
	s_add_u32 m0, s10, 0x4800
	v_mfma_f32_32x32x16_bf16 v[34:49], v[90:93], v[86:89], v[34:49]
	global_load_lds_dwordx4 v100, s[8:9]
	s_add_u32 m0, s10, 0x4c00
	v_mfma_f32_32x32x16_bf16 v[50:65], v[94:97], v[86:89], v[50:65]
	global_load_lds_dwordx4 v101, s[8:9]
	s_add_u32 s8, s8, 128
	s_addc_u32 s9, s9, 0
	ds_read_b128 v[82:85], v105 offset:32768
	ds_read_b128 v[90:93], v109 offset:32768
	ds_read_b128 v[86:89], v105 offset:36864
	ds_read_b128 v[94:97], v109 offset:36864
	s_waitcnt lgkmcnt(4)
	v_mfma_f32_32x32x16_bf16 v[2:17], v[74:77], v[66:69], v[2:17]
	v_mfma_f32_32x32x16_bf16 v[18:33], v[78:81], v[66:69], v[18:33]
	v_mfma_f32_32x32x16_bf16 v[34:49], v[74:77], v[70:73], v[34:49]
	v_mfma_f32_32x32x16_bf16 v[50:65], v[78:81], v[70:73], v[50:65]
	s_waitcnt lgkmcnt(0)
	s_barrier
	v_mfma_f32_32x32x16_bf16 v[2:17], v[90:93], v[82:85], v[2:17]
	v_mfma_f32_32x32x16_bf16 v[18:33], v[94:97], v[82:85], v[18:33]
	v_mfma_f32_32x32x16_bf16 v[34:49], v[90:93], v[86:89], v[34:49]
	v_mfma_f32_32x32x16_bf16 v[50:65], v[94:97], v[86:89], v[50:65]
	s_branch .Lip_kdone
